# L0 attention: the 1280 small units (context-query MLA + windowed GQA) handed out in XCD-contiguous blocks of 6/6/5/5/5/5/4/4 per WG by measured group speed rank (on keep_v8)
# baseline (speedup 1.0000x reference)
.LBB0_512:
	s_or_b64 exec, exec, s[2:3]
	v_readlane_b32 s2, v255, 0
	v_readlane_b32 s4, v255, 34
	s_waitcnt lgkmcnt(0)
	s_barrier
	v_mbcnt_lo_u32_b32 v2, -1, 0
	v_mbcnt_hi_u32_b32 v2, -1, v2
	v_readlane_b32 s5, v255, 35
	v_add_u32_e32 v0, s2, v2
	s_mov_b64 s[16:17], s[0:1]
	v_readfirstlane_b32 s2, v0
	s_andn2_b64 vcc, exec, s[4:5]
	s_cbranch_vccnz .LBB0_617
	s_load_dwordx4 s[12:15], s[16:17], 0x120
	s_ashr_i32 s3, s2, 6
	v_and_b32_e32 v3, 63, v2
	v_bfe_u32 v5, v2, 5, 1
	v_lshlrev_b32_e32 v3, 2, v3
	s_waitcnt lgkmcnt(0)
	s_add_u32 s18, s14, 0x10f00000
	s_addc_u32 s19, s15, 0
	s_add_u32 s40, s14, 0x19600000
	s_addc_u32 s41, s15, 0
	s_ashr_i32 s42, s2, 7
	s_lshl_b32 s43, s3, 5
	s_add_u32 s44, s14, 0xac00740
	s_addc_u32 s45, s15, 0
	s_add_u32 s46, s14, 0xac00840
	s_mulk_i32 s3, 0x1200
	s_addc_u32 s47, s15, 0
	s_add_i32 s2, s3, 0
	s_add_i32 s2, s2, 0x10000
	v_and_b32_e32 v119, 31, v2
	v_lshrrev_b32_e32 v4, 2, v2
	v_lshlrev_b32_e32 v125, 2, v5
	v_xor_b32_e32 v146, 0x80, v3
	v_mov_b32_e32 v3, s2
	s_movk_i32 s3, 0x90
	v_and_b32_e32 v118, 8, v4
	v_and_or_b32 v4, v4, 3, v125
	v_lshlrev_b32_e32 v6, 1, v2
	v_lshlrev_b32_e32 v7, 3, v2
	v_mad_u32_u24 v147, v119, s3, v3
	v_and_b32_e32 v3, 7, v2
	v_mul_u32_u24_e32 v4, 0xc0, v4
	v_and_b32_e32 v6, 32, v6
	v_and_b32_e32 v7, 24, v7
	v_lshl_add_u32 v156, v3, 4, s2
	v_bfe_u32 v2, v2, 3, 3
	s_mov_b32 s2, 0x2aaaaaab
	v_or3_b32 v127, v4, v6, v7
	v_mul_u32_u24_e32 v4, 0x90, v119
	v_mul_u32_u24_e32 v157, 0x90, v2
	v_lshlrev_b32_e32 v124, 10, v2
	v_mul_hi_i32 v2, v0, s2
	v_lshl_add_u32 v129, v5, 4, v4
	v_ashrrev_i32_e32 v4, 31, v0
	v_lshlrev_b32_e32 v122, 3, v3
	v_lshrrev_b32_e32 v3, 31, v2
	v_ashrrev_i32_e32 v2, 1, v2
	v_lshrrev_b32_e32 v4, 29, v4
	v_add_u32_e32 v159, v2, v3
	v_add_u32_e32 v4, v0, v4
	s_movk_i32 s3, 0xd0
	v_mul_lo_u32 v3, v159, 12
	v_ashrrev_i32_e32 v131, 3, v4
	v_and_b32_e32 v4, 0x1ffffff8, v4
	v_mul_lo_u32 v2, v159, s3
	v_sub_u32_e32 v3, v0, v3
	v_sub_u32_e32 v4, v0, v4
	v_lshl_add_u32 v160, v3, 4, v2
	v_add_u32_e32 v2, 0x200, v0
	v_lshlrev_b32_e32 v5, 4, v0
	v_lshlrev_b32_e32 v120, 3, v4
	v_mul_hi_i32 v4, v2, s2
	v_lshl_add_u32 v145, v131, 6, v5
	v_lshrrev_b32_e32 v5, 31, v4
	v_ashrrev_i32_e32 v4, 1, v4
	v_add_u32_e32 v161, v4, v5
	v_mul_lo_u32 v5, v161, 12
	v_sub_u32_e32 v2, v2, v5
	v_mul_lo_u32 v4, v161, s3
	s_movk_i32 s2, 0x300
	v_lshlrev_b32_e32 v132, 3, v3
	s_movk_i32 s4, 0x100
	v_lshlrev_b32_e32 v134, 3, v2
	v_and_or_b32 v123, s43, 32, v119
	v_add_lshl_u32 v144, v131, v0, 4
	v_ashrrev_i32_e32 v121, 31, v120
	v_or_b32_e32 v126, 0x2000, v124
	v_or_b32_e32 v128, 0x4000, v124
	v_or_b32_e32 v130, 0x6000, v124
	v_lshl_add_u32 v158, v119, 6, v129
	v_lshl_add_u32 v162, v2, 4, v4
	v_cmp_gt_i32_e64 s[2:3], s2, v0
	v_ashrrev_i32_e32 v133, 31, v132
	v_cmp_gt_i32_e64 s[4:5], s4, v0
	v_ashrrev_i32_e32 v135, 31, v134
	v_readlane_b32 s48, v255, 51
	v_readlane_b32 s49, v255, 50
	s_nop 3
	s_mov_b32 s98, s33
	s_movk_i32 s99, 0x8ff
	s_cmpk_lg_u32 s33, 0x100
	s_cbranch_scc1 .La0_done
	s_load_dwordx2 s[100:101], s[0:1], 0x128
	s_and_b32 s98, s8, 7
	s_lshl_b32 s98, s98, 8
	s_waitcnt lgkmcnt(0)
	s_add_u32 s100, s100, s98
	s_addc_u32 s101, s101, 0
	s_add_u32 s100, s100, 0x302400
	s_addc_u32 s101, s101, 0
	global_load_dword v253, v1, s[100:101] sc1
	s_waitcnt vmcnt(0)
	v_readfirstlane_b32 s101, v253
	s_nop 3
	s_and_b32 s101, s101, 7
	s_mul_i32 s100, s101, 6
	s_sub_i32 s98, s101, 2
	s_max_i32 s98, s98, 0
	s_sub_i32 s100, s100, s98
	s_sub_i32 s98, s101, 6
	s_max_i32 s98, s98, 0
	s_sub_i32 s100, s100, s98
	s_cmp_ge_u32 s101, 2
	s_cselect_b32 s98, 5, 6
	s_cmp_ge_u32 s101, 6
	s_cselect_b32 s99, 1, 0
	s_sub_i32 s99, s98, s99
	s_lshl_b32 s100, s100, 5
	s_addk_i32 s100, 0x400
	s_lshl_b32 s99, s99, 5
	s_add_i32 s99, s99, s100
	s_add_i32 s99, s99, -1
	s_lshr_b32 s98, s8, 3
	s_add_i32 s100, s100, s98
	s_movk_i32 s98, 0x100

.LBB0_515:
	s_add_i32 s49, s49, s98
	s_add_i32 s48, s48, s98
	s_cmpk_lg_u32 s98, 0x100
	s_cbranch_scc1 .La0_chk
	s_cmpk_lt_i32 s49, 0x400
	s_cbranch_scc1 .LBB0_516
	s_sub_i32 s101, s100, s49
	s_mov_b32 s49, s100
	s_add_i32 s48, s48, s101
	s_movk_i32 s98, 0x20
.La0_chk:
	s_cmp_gt_i32 s49, s99
	s_cbranch_scc1 .LBB0_617
